# attention: K-fragment ds_reads of the first step after each workgroup barrier hoisted above the global-load address block / previous row-sum tail (on top of nop-fill)
# speedup vs baseline: 1.0059x; 1.0004x over previous
; #define MFMA(a, b, c) __builtin_amdgcn_mfma_f32_32x32x16_bf16((a), (b), (c), 0, 0, 0)
; DI float fexp2(float x) { return __builtin_amdgcn_exp2f(x); }
; DI f32x16 zero16() { f32x16 z; for (int i = 0; i < 16; ++i) z[i] = 0.f; return z; }
; DI void phase_attn(const Params& p, int hf, bool skipctx, char* smem, int& rot) {
;     ...
;     auto compute = [&](int buf, int half) {
;       const char* sk = smem + buf * STG + half * 64 * KROW; const char* sv = smem + buf * STG + KB_ + half * 128;
;       f32x16 st[2]; st[0] = zero16(); st[1] = zero16();
;       {
;         bf16x8 kf[2][6];
; #pragma unroll
;         for (int kb = 0; kb < 2; ++kb)
; #pragma unroll
;           for (int ks = 0; ks < 6; ++ks) kf[kb][ks] = *(const bf16x8*)(sk + (kb * 32 + r) * KROW + (ks * 16 + h * 8) * 2);
;         __builtin_amdgcn_sched_barrier(0);
; #pragma unroll
;         for (int ks = 0; ks < 6; ++ks)
; #pragma unroll
;           for (int kb = 0; kb < 2; ++kb) st[kb] = MFMA(kf[kb][ks], qf[ks], st[kb]);
;         __builtin_amdgcn_sched_barrier(0);
;       }
;       bf16x8 vf[2][2][2];
; #pragma unroll
;       for (int kb = 0; kb < 2; ++kb)
; #pragma unroll
;         for (int s2 = 0; s2 < 2; ++s2)
; #pragma unroll
;           for (int dvb = 0; dvb < 2; ++dvb) {
;             const char* vp = sv + (dvb * 32 + r) * VROW + (kb * 32 + 16 * s2 + 4 * h) * 2;
;             const s16x4 lo = *(const s16x4*)vp, hi = *(const s16x4*)(vp + 16);
;             vf[kb][s2][dvb] = __builtin_shufflevector(lo, hi, 0, 1, 2, 3, 4, 5, 6, 7);
;           }
;       float mx = st[0][0];
; #pragma unroll
;       for (int i = 0; i < 16; ++i) { mx = fmaxf(mx, st[0][i]); mx = fmaxf(mx, st[1][i]); }
;       if (__any(mx > m_run + 8.f)) {
;         mx = fmaxf(mx, __shfl_xor(mx, 32));
;         const float m_new = fmaxf(m_run, mx);
;         const float alpha = fexp2(m_run - m_new);
;         m_run = m_new;
;         l_run *= alpha;
; #pragma unroll
;         for (int i = 0; i < 16; ++i) { o[0][i] *= alpha; o[1][i] *= alpha; }
;       }
;     ...
;     for (int kt = 0; kt < nkt; kt += 2) {
;       if (kt + 2 < nkt) ATT_LOAD(ak0, ak1, ak2, av0, av1, kt + 2);
;       compute(0, 0); compute(0, 1);
.LBB0_795:
	ds_read_b128 v[32:35], v190
	ds_read_b128 v[128:131], v190 offset:32
	ds_read_b128 v[132:135], v190 offset:64
	ds_read_b128 v[136:139], v190 offset:96
	ds_read_b128 v[140:143], v190 offset:128
	ds_read_b128 v[144:147], v190 offset:160
	ds_read_b128 v[36:39], v190 offset:6656
	ds_read_b128 v[148:151], v190 offset:6688
	ds_read_b128 v[152:155], v190 offset:6720
	ds_read_b128 v[156:159], v190 offset:6752
	ds_read_b128 v[214:217], v190 offset:6784
	ds_read_b128 v[234:237], v190 offset:6816
	s_add_i32 s15, s4, 2
	s_cmp_lt_u32 s15, s13
	s_cselect_b64 s[36:37], -1, 0
	s_cmp_ge_u32 s15, s13
	s_cselect_b64 s[26:27], -1, 0
	s_and_b64 vcc, exec, s[26:27]
	s_cbranch_vccnz .LBB0_797
	v_lshl_add_u64 v[200:201], s[94:95], 0, v[174:175]
	v_add_co_u32_e32 v200, vcc, 0x18b28000, v200
	v_lshl_add_u64 v[202:203], s[94:95], 0, v[172:173]
	s_nop 0
	v_addc_co_u32_e32 v201, vcc, 0, v201, vcc
	v_add_co_u32_e32 v202, vcc, 0x18b28000, v202
	s_nop 1
	v_addc_co_u32_e32 v203, vcc, 0, v203, vcc
	global_load_dwordx4 v[76:79], v[200:201], off
	global_load_dwordx4 v[80:83], v[202:203], off
	v_lshl_add_u64 v[200:201], s[94:95], 0, v[170:171]
	v_add_co_u32_e32 v200, vcc, 0x18b28000, v200
	v_lshl_add_u64 v[202:203], s[94:95], 0, v[166:167]
	s_nop 0
	v_addc_co_u32_e32 v201, vcc, 0, v201, vcc
	global_load_dwordx4 v[84:87], v[200:201], off
	global_load_dwordx4 v[92:95], v[202:203], off offset:-256
	v_lshl_add_u64 v[200:201], s[94:95], 0, v[168:169]
	global_load_dwordx4 v[104:107], v[200:201], off offset:-256
.LBB0_797:
	s_waitcnt lgkmcnt(11)
	v_mfma_f32_32x32x16_bf16 v[48:63], v[32:35], v[64:67], 0
	s_waitcnt lgkmcnt(5)
	v_mfma_f32_32x32x16_bf16 v[32:47], v[36:39], v[64:67], 0
	v_mfma_f32_32x32x16_bf16 v[48:63], v[128:131], v[68:71], v[48:63]
	s_waitcnt lgkmcnt(4)
	v_mfma_f32_32x32x16_bf16 v[32:47], v[148:151], v[68:71], v[32:47]
	v_mfma_f32_32x32x16_bf16 v[48:63], v[132:135], v[72:75], v[48:63]
	s_waitcnt lgkmcnt(3)
	v_mfma_f32_32x32x16_bf16 v[32:47], v[152:155], v[72:75], v[32:47]
	v_mfma_f32_32x32x16_bf16 v[48:63], v[136:139], v[88:91], v[48:63]
	s_waitcnt lgkmcnt(2)
	v_mfma_f32_32x32x16_bf16 v[32:47], v[156:159], v[88:91], v[32:47]
	v_mfma_f32_32x32x16_bf16 v[48:63], v[140:143], v[96:99], v[48:63]
	s_waitcnt lgkmcnt(1)
	v_mfma_f32_32x32x16_bf16 v[32:47], v[214:217], v[96:99], v[32:47]
	v_mfma_f32_32x32x16_bf16 v[48:63], v[144:147], v[100:103], v[48:63]
	s_waitcnt lgkmcnt(0)
	v_mfma_f32_32x32x16_bf16 v[32:47], v[234:237], v[100:103], v[32:47]
	s_nop 1
	v_add_u32_e32 v214, 0x6800, v191
	v_add_u32_e32 v215, 0x8800, v191
	ds_read2_b64 v[156:159], v214 offset1:2
	ds_read2_b64 v[148:151], v214 offset0:4 offset1:6
	ds_read2_b64 v[152:155], v215 offset0:32 offset1:34
	ds_read2_b64 v[144:147], v215 offset0:36 offset1:38
	ds_read2_b64 v[140:143], v214 offset0:8 offset1:10
	ds_read2_b64 v[136:139], v215 offset0:40 offset1:42
	ds_read2_b64 v[132:135], v214 offset0:12 offset1:14
	ds_read2_b64 v[128:131], v215 offset0:44 offset1:46
	v_max_f32_e32 v195, v32, v32
	v_max_f32_e32 v200, v48, v48
	v_max_f32_e32 v195, v200, v195
	v_max3_f32 v195, v195, v49, v33
	v_max3_f32 v195, v195, v50, v34
	v_max3_f32 v195, v195, v51, v35
	v_max3_f32 v195, v195, v52, v36
	v_max3_f32 v195, v195, v53, v37
	v_max3_f32 v195, v195, v54, v38
	v_max3_f32 v195, v195, v55, v39
	v_max3_f32 v195, v195, v56, v40
	v_max3_f32 v195, v195, v57, v41
	v_max3_f32 v195, v195, v58, v42
	v_max3_f32 v195, v195, v59, v43
	v_max3_f32 v195, v195, v60, v44
	v_max3_f32 v195, v195, v61, v45
	v_max3_f32 v195, v195, v62, v46
	v_max3_f32 v217, v195, v63, v47
	v_add_f32_e32 v216, 0x41000000, v212
	v_cmp_gt_f32_e32 vcc, v217, v216
	s_cbranch_vccz .LBB0_799
	v_cmp_lt_i32_e32 vcc, v224, v207
	s_nop 1
	v_cndmask_b32_e32 v195, v205, v224, vcc
	v_lshlrev_b32_e32 v195, 2, v195
	ds_bpermute_b32 v195, v195, v217
	s_waitcnt lgkmcnt(0)
	v_max3_f32 v195, v212, v217, v195
	v_sub_f32_e32 v200, v212, v195
	v_exp_f32_e32 v200, v200
	v_add_f32_e32 v216, 0x41000000, v195
	v_mov_b32_e32 v212, v195
	v_mul_f32_e32 v213, v213, v200
	v_pk_mul_f32 v[30:31], v[30:31], v[200:201] op_sel_hi:[1,0]
	v_pk_mul_f32 v[28:29], v[28:29], v[200:201] op_sel_hi:[1,0]
	v_pk_mul_f32 v[26:27], v[26:27], v[200:201] op_sel_hi:[1,0]
	v_pk_mul_f32 v[24:25], v[24:25], v[200:201] op_sel_hi:[1,0]
	v_pk_mul_f32 v[22:23], v[22:23], v[200:201] op_sel_hi:[1,0]
	v_pk_mul_f32 v[20:21], v[20:21], v[200:201] op_sel_hi:[1,0]
	v_pk_mul_f32 v[18:19], v[18:19], v[200:201] op_sel_hi:[1,0]
	v_pk_mul_f32 v[16:17], v[16:17], v[200:201] op_sel_hi:[1,0]
	v_pk_mul_f32 v[14:15], v[14:15], v[200:201] op_sel_hi:[1,0]
	v_pk_mul_f32 v[12:13], v[12:13], v[200:201] op_sel_hi:[1,0]
	v_pk_mul_f32 v[10:11], v[10:11], v[200:201] op_sel_hi:[1,0]
	v_pk_mul_f32 v[8:9], v[8:9], v[200:201] op_sel_hi:[1,0]
	v_pk_mul_f32 v[6:7], v[6:7], v[200:201] op_sel_hi:[1,0]
	v_pk_mul_f32 v[4:5], v[4:5], v[200:201] op_sel_hi:[1,0]
	v_pk_mul_f32 v[2:3], v[2:3], v[200:201] op_sel_hi:[1,0]
	v_pk_mul_f32 v[0:1], v[0:1], v[200:201] op_sel_hi:[1,0]

; #define MFMA(a, b, c) __builtin_amdgcn_mfma_f32_32x32x16_bf16((a), (b), (c), 0, 0, 0)
; DI float fexp2(float x) { return __builtin_amdgcn_exp2f(x); }
; DI void phase_attn(const Params& p, int hf, bool skipctx, char* smem, int& rot) {
;     ...
;       float ps = 0.f;
; #pragma unroll
;       for (int kb = 0; kb < 2; ++kb)
; #pragma unroll
;         for (int i = 0; i < 16; ++i) { const float e = fexp2(st[kb][i] - m_run); st[kb][i] = e; ps += e; }
;       l_run += ps;
; #pragma unroll
;       for (int kb = 0; kb < 2; ++kb)
; #pragma unroll
;         for (int s2 = 0; s2 < 2; ++s2) {
;           const bf16x8 pb = pack8(st[kb][8 * s2 + 0], st[kb][8 * s2 + 1], st[kb][8 * s2 + 2], st[kb][8 * s2 + 3], st[kb][8 * s2 + 4], st[kb][8 * s2 + 5], st[kb][8 * s2 + 6], st[kb][8 * s2 + 7]);
; #pragma unroll
;           for (int dvb = 0; dvb < 2; ++dvb) o[dvb] = MFMA(vf[kb][s2][dvb], pb, o[dvb]);
;         }
;     };
;     __syncthreads();
;     ATT_LOAD(ak0, ak1, ak2, av0, av1, 0);
;     ATT_LOAD(bk0, bk1, bk2, bv0, bv1, 1);
;     ATT_WRITE(ak0, ak1, ak2, av0, av1, 0);
;     __syncthreads();
;     for (int kt = 0; kt < nkt; kt += 2) {
;       if (kt + 2 < nkt) ATT_LOAD(ak0, ak1, ak2, av0, av1, kt + 2);
;       compute(0, 0); compute(0, 1);
;       ATT_WRITE(bk0, bk1, bk2, bv0, bv1, 1);
;       __syncthreads();
;       if (kt + 3 < nkt) ATT_LOAD(bk0, bk1, bk2, bv0, bv1, kt + 3);
;       compute(1, 0); compute(1, 1);
.LBB0_801:
	v_sub_f32_e32 v48, v48, v212
	v_sub_f32_e32 v49, v49, v212
	v_sub_f32_e32 v50, v50, v212
	v_sub_f32_e32 v51, v51, v212
	v_sub_f32_e32 v52, v52, v212
	v_sub_f32_e32 v53, v53, v212
	v_sub_f32_e32 v54, v54, v212
	v_sub_f32_e32 v55, v55, v212
	v_exp_f32_e32 v48, v48
	v_exp_f32_e32 v49, v49
	v_exp_f32_e32 v50, v50
	v_exp_f32_e32 v51, v51
	v_exp_f32_e32 v52, v52
	v_exp_f32_e32 v53, v53
	v_exp_f32_e32 v54, v54
	v_exp_f32_e32 v55, v55
	v_cvt_pk_bf16_f32 v214, v48, v49
	v_cvt_pk_bf16_f32 v215, v50, v51
	v_cvt_pk_bf16_f32 v216, v52, v53
	v_cvt_pk_bf16_f32 v217, v54, v55
	v_sub_f32_e32 v56, v56, v212
	v_sub_f32_e32 v57, v57, v212
	s_waitcnt lgkmcnt(7)
	v_mfma_f32_32x32x16_bf16 v[16:31], v[156:159], v[214:217], v[16:31]
	v_sub_f32_e32 v58, v58, v212
	v_sub_f32_e32 v59, v59, v212
	v_sub_f32_e32 v60, v60, v212
	v_sub_f32_e32 v61, v61, v212
	v_sub_f32_e32 v62, v62, v212
	v_sub_f32_e32 v63, v63, v212
	v_exp_f32_e32 v56, v56
	s_waitcnt lgkmcnt(5)
	v_mfma_f32_32x32x16_bf16 v[0:15], v[152:155], v[214:217], v[0:15]
	v_exp_f32_e32 v57, v57
	v_exp_f32_e32 v58, v58
	v_exp_f32_e32 v59, v59
	v_exp_f32_e32 v60, v60
	v_exp_f32_e32 v61, v61
	v_exp_f32_e32 v62, v62
	v_exp_f32_e32 v63, v63
	v_cvt_pk_bf16_f32 v152, v56, v57
	v_cvt_pk_bf16_f32 v153, v58, v59
	v_cvt_pk_bf16_f32 v154, v60, v61
	v_cvt_pk_bf16_f32 v155, v62, v63
	v_sub_f32_e32 v32, v32, v212
	v_sub_f32_e32 v33, v33, v212
	v_mfma_f32_32x32x16_bf16 v[16:31], v[148:151], v[152:155], v[16:31]
	v_sub_f32_e32 v34, v34, v212
	v_sub_f32_e32 v35, v35, v212
	v_sub_f32_e32 v36, v36, v212
	v_sub_f32_e32 v37, v37, v212
	v_sub_f32_e32 v38, v38, v212
	v_sub_f32_e32 v39, v39, v212
	v_exp_f32_e32 v32, v32
	s_waitcnt lgkmcnt(4)
	v_mfma_f32_32x32x16_bf16 v[0:15], v[144:147], v[152:155], v[0:15]
	v_exp_f32_e32 v33, v33
	v_exp_f32_e32 v34, v34
	v_exp_f32_e32 v35, v35
	v_exp_f32_e32 v36, v36
	v_exp_f32_e32 v37, v37
	v_exp_f32_e32 v38, v38
	v_exp_f32_e32 v39, v39
	v_cvt_pk_bf16_f32 v144, v32, v33
	v_cvt_pk_bf16_f32 v145, v34, v35
	v_cvt_pk_bf16_f32 v146, v36, v37
	v_cvt_pk_bf16_f32 v147, v38, v39
	v_sub_f32_e32 v40, v40, v212
	v_sub_f32_e32 v41, v41, v212
	s_waitcnt lgkmcnt(3)
	v_mfma_f32_32x32x16_bf16 v[16:31], v[140:143], v[144:147], v[16:31]
	v_sub_f32_e32 v42, v42, v212
	v_sub_f32_e32 v43, v43, v212
	v_sub_f32_e32 v44, v44, v212
	v_sub_f32_e32 v45, v45, v212
	v_sub_f32_e32 v46, v46, v212
	v_sub_f32_e32 v47, v47, v212
	v_exp_f32_e32 v40, v40
	s_waitcnt lgkmcnt(2)
	v_mfma_f32_32x32x16_bf16 v[0:15], v[136:139], v[144:147], v[0:15]
	v_exp_f32_e32 v41, v41
	v_exp_f32_e32 v42, v42
	v_exp_f32_e32 v43, v43
	v_exp_f32_e32 v44, v44
	v_exp_f32_e32 v45, v45
	v_exp_f32_e32 v46, v46
	v_exp_f32_e32 v47, v47
	v_cvt_pk_bf16_f32 v136, v40, v41
	v_cvt_pk_bf16_f32 v137, v42, v43
	v_cvt_pk_bf16_f32 v138, v44, v45
	v_cvt_pk_bf16_f32 v139, v46, v47
	s_add_i32 s4, s4, 3
	s_cmp_ge_u32 s4, s13
	s_waitcnt lgkmcnt(1)
	v_mfma_f32_32x32x16_bf16 v[16:31], v[128:131], v[136:139], v[16:31]
	s_waitcnt vmcnt(1)
	ds_write_b128 v176, v[112:115] offset:43520
	ds_write_b128 v177, v[108:111] offset:43520
	ds_write_b128 v178, v[116:119] offset:43520
	ds_write2_b64 v186, v[120:121], v[122:123] offset1:1
	s_waitcnt vmcnt(0)
	ds_write2_b64 v187, v[124:125], v[126:127] offset1:1
	s_waitcnt lgkmcnt(0)
	s_barrier
	v_mfma_f32_32x32x16_bf16 v[0:15], v[132:135], v[136:139], v[0:15]
	ds_read_b128 v[238:241], v190 offset:43520
	ds_read_b128 v[128:131], v190 offset:43552
	ds_read_b128 v[132:135], v190 offset:43584
	ds_read_b128 v[136:139], v190 offset:43616
	ds_read_b128 v[140:143], v190 offset:43648
	ds_read_b128 v[144:147], v190 offset:43680
	ds_read_b128 v[242:245], v190 offset:50176
	ds_read_b128 v[148:151], v190 offset:50208
	ds_read_b128 v[152:155], v190 offset:50240
	ds_read_b128 v[156:159], v190 offset:50272
	ds_read_b128 v[214:217], v190 offset:50304
	ds_read_b128 v[234:237], v190 offset:50336
	s_cbranch_scc1 .LBB0_803
	v_lshl_add_u64 v[108:109], s[94:95], 0, v[174:175]
	v_add_co_u32_e32 v108, vcc, 0x18b2e000, v108
	v_lshl_add_u64 v[110:111], s[94:95], 0, v[172:173]
	s_nop 0
	v_addc_co_u32_e32 v109, vcc, 0, v109, vcc
	v_add_co_u32_e32 v110, vcc, 0x18b2e000, v110
	v_lshl_add_u64 v[116:117], s[94:95], 0, v[170:171]
	s_nop 0
	v_addc_co_u32_e32 v111, vcc, 0, v111, vcc
	v_add_co_u32_e32 v116, vcc, 0x18b2e000, v116
	v_lshl_add_u64 v[120:121], s[94:95], 0, v[166:167]
	s_nop 0
	v_addc_co_u32_e32 v117, vcc, 0, v117, vcc
	v_lshl_add_u64 v[124:125], s[94:95], 0, v[168:169]
	global_load_dwordx4 v[112:115], v[108:109], off
	s_nop 0
	global_load_dwordx4 v[108:111], v[110:111], off
	s_nop 0
	global_load_dwordx4 v[116:119], v[116:117], off
	s_nop 0
	global_load_dwordx4 v[120:123], v[120:121], off
	s_nop 0
	global_load_dwordx4 v[124:127], v[124:125], off
; #define MFMA(a, b, c) __builtin_amdgcn_mfma_f32_32x32x16_bf16((a), (b), (c), 0, 0, 0)
; DI float fexp2(float x) { return __builtin_amdgcn_exp2f(x); }
; DI void phase_attn(const Params& p, int hf, bool skipctx, char* smem, int& rot) {
;     ...
; #pragma unroll
;         for (int kb = 0; kb < 2; ++kb)
; #pragma unroll
;           for (int ks = 0; ks < 6; ++ks) kf[kb][ks] = *(const bf16x8*)(sk + (kb * 32 + r) * KROW + (ks * 16 + h * 8) * 2);
;         __builtin_amdgcn_sched_barrier(0);
; #pragma unroll
;         for (int ks = 0; ks < 6; ++ks)
; #pragma unroll
;           for (int kb = 0; kb < 2; ++kb) st[kb] = MFMA(kf[kb][ks], qf[ks], st[kb]);
;         __builtin_amdgcn_sched_barrier(0);
;       }
;       bf16x8 vf[2][2][2];
; #pragma unroll
;       for (int kb = 0; kb < 2; ++kb)
; #pragma unroll
;         for (int s2 = 0; s2 < 2; ++s2)
; #pragma unroll
;           for (int dvb = 0; dvb < 2; ++dvb) {
;             const char* vp = sv + (dvb * 32 + r) * VROW + (kb * 32 + 16 * s2 + 4 * h) * 2;
;             const s16x4 lo = *(const s16x4*)vp, hi = *(const s16x4*)(vp + 16);
;             vf[kb][s2][dvb] = __builtin_shufflevector(lo, hi, 0, 1, 2, 3, 4, 5, 6, 7);
;           }
;       float mx = st[0][0];
; #pragma unroll
;       for (int i = 0; i < 16; ++i) { mx = fmaxf(mx, st[0][i]); mx = fmaxf(mx, st[1][i]); }
;       if (__any(mx > m_run + 8.f)) {
;         mx = fmaxf(mx, __shfl_xor(mx, 32));
;         const float m_new = fmaxf(m_run, mx);
;         const float alpha = fexp2(m_run - m_new);
;         m_run = m_new;
;         l_run *= alpha;
; #pragma unroll
;         for (int i = 0; i < 16; ++i) { o[0][i] *= alpha; o[1][i] *= alpha; }
;       }
;     ...
;         for (int i = 0; i < 16; ++i) { const float e = fexp2(st[kb][i] - m_run); st[kb][i] = e; ps += e; }
;       l_run += ps;
.LBB0_803:
	v_add_f32_e32 v48, 0, v48
	v_add_f32_e32 v48, v49, v48
	v_add_f32_e32 v48, v50, v48
	v_add_f32_e32 v48, v51, v48
	v_add_f32_e32 v48, v52, v48
	v_add_f32_e32 v48, v53, v48
	v_add_f32_e32 v48, v54, v48
	v_add_f32_e32 v48, v55, v48
	v_add_f32_e32 v48, v56, v48
	v_add_f32_e32 v48, v57, v48
	v_add_f32_e32 v48, v58, v48
	v_add_f32_e32 v48, v59, v48
	v_add_f32_e32 v48, v60, v48
	v_add_f32_e32 v48, v61, v48
	v_add_f32_e32 v48, v62, v48
	v_add_f32_e32 v48, v63, v48
	v_add_f32_e32 v32, v32, v48
	v_add_f32_e32 v32, v33, v32
	v_add_f32_e32 v32, v34, v32
	v_add_f32_e32 v32, v35, v32
	v_add_f32_e32 v32, v36, v32
	v_add_f32_e32 v32, v37, v32
	v_add_f32_e32 v32, v38, v32
	v_add_f32_e32 v32, v39, v32
	v_add_f32_e32 v32, v40, v32
	v_add_f32_e32 v32, v41, v32
	v_add_f32_e32 v32, v42, v32
	v_add_f32_e32 v32, v43, v32
	v_add_f32_e32 v32, v44, v32
	v_add_f32_e32 v32, v45, v32
	v_add_f32_e32 v32, v46, v32
	v_add_f32_e32 v32, v47, v32
	v_add_f32_e32 v213, v213, v32
	s_waitcnt lgkmcnt(11)
	v_mfma_f32_32x32x16_bf16 v[48:63], v[238:241], v[64:67], 0
	s_waitcnt lgkmcnt(5)
	v_mfma_f32_32x32x16_bf16 v[32:47], v[242:245], v[64:67], 0
	v_mfma_f32_32x32x16_bf16 v[48:63], v[128:131], v[68:71], v[48:63]
	s_waitcnt lgkmcnt(4)
	v_mfma_f32_32x32x16_bf16 v[32:47], v[148:151], v[68:71], v[32:47]
	v_mfma_f32_32x32x16_bf16 v[48:63], v[132:135], v[72:75], v[48:63]
	s_waitcnt lgkmcnt(3)
	v_mfma_f32_32x32x16_bf16 v[32:47], v[152:155], v[72:75], v[32:47]
	v_mfma_f32_32x32x16_bf16 v[48:63], v[136:139], v[88:91], v[48:63]
	s_waitcnt lgkmcnt(2)
	v_mfma_f32_32x32x16_bf16 v[32:47], v[156:159], v[88:91], v[32:47]
	v_mfma_f32_32x32x16_bf16 v[48:63], v[140:143], v[96:99], v[48:63]
	s_waitcnt lgkmcnt(1)
	v_mfma_f32_32x32x16_bf16 v[32:47], v[214:217], v[96:99], v[32:47]
	v_mfma_f32_32x32x16_bf16 v[48:63], v[144:147], v[100:103], v[48:63]
	s_waitcnt lgkmcnt(0)
	v_mfma_f32_32x32x16_bf16 v[32:47], v[234:237], v[100:103], v[32:47]
	v_add_u32_e32 v128, 0x2000, v188
	ds_read2_b64 v[152:155], v128 offset0:32 offset1:34
	v_add_u32_e32 v128, v184, v181
	ds_read2_b64 v[156:159], v188 offset1:2
	ds_read2_b64 v[148:151], v128 offset1:2
	ds_read2_b64 v[144:147], v194 offset0:32 offset1:34
	v_add_u32_e32 v128, v184, v182
	ds_read2_b64 v[140:143], v128 offset1:2
	ds_read2_b64 v[136:139], v204 offset0:32 offset1:34
	v_add_u32_e32 v128, v184, v183
	ds_read2_b64 v[132:135], v128 offset1:2
	ds_read2_b64 v[128:131], v206 offset0:32 offset1:34
	v_max_f32_e32 v195, v32, v32
	v_max_f32_e32 v200, v48, v48
	v_max_f32_e32 v195, v200, v195
	v_max3_f32 v195, v195, v49, v33
	v_max3_f32 v195, v195, v50, v34
	v_max3_f32 v195, v195, v51, v35
	v_max3_f32 v195, v195, v52, v36
	v_max3_f32 v195, v195, v53, v37
	v_max3_f32 v195, v195, v54, v38
	v_max3_f32 v195, v195, v55, v39
	v_max3_f32 v195, v195, v56, v40
	v_max3_f32 v195, v195, v57, v41
	v_max3_f32 v195, v195, v58, v42
	v_max3_f32 v195, v195, v59, v43
	v_max3_f32 v195, v195, v60, v44
	v_max3_f32 v195, v195, v61, v45
	v_max3_f32 v195, v195, v62, v46
	v_max3_f32 v215, v195, v63, v47
	v_add_f32_e32 v214, 0x41000000, v212
	v_cmp_gt_f32_e32 vcc, v215, v214
	s_cbranch_vccz .LBB0_805
	v_cmp_lt_i32_e32 vcc, v224, v207
	s_nop 1
	v_cndmask_b32_e32 v195, v205, v224, vcc
	v_lshlrev_b32_e32 v195, 2, v195
	ds_bpermute_b32 v195, v195, v215
	s_waitcnt lgkmcnt(0)
	v_max3_f32 v195, v212, v215, v195
	v_sub_f32_e32 v200, v212, v195
	v_exp_f32_e32 v200, v200
	v_add_f32_e32 v214, 0x41000000, v195
	v_mov_b32_e32 v212, v195
	v_mul_f32_e32 v213, v213, v200
	v_pk_mul_f32 v[30:31], v[30:31], v[200:201] op_sel_hi:[1,0]
	v_pk_mul_f32 v[28:29], v[28:29], v[200:201] op_sel_hi:[1,0]
	v_pk_mul_f32 v[26:27], v[26:27], v[200:201] op_sel_hi:[1,0]
	v_pk_mul_f32 v[24:25], v[24:25], v[200:201] op_sel_hi:[1,0]
	v_pk_mul_f32 v[22:23], v[22:23], v[200:201] op_sel_hi:[1,0]
	v_pk_mul_f32 v[20:21], v[20:21], v[200:201] op_sel_hi:[1,0]
	v_pk_mul_f32 v[18:19], v[18:19], v[200:201] op_sel_hi:[1,0]
	v_pk_mul_f32 v[16:17], v[16:17], v[200:201] op_sel_hi:[1,0]
	v_pk_mul_f32 v[14:15], v[14:15], v[200:201] op_sel_hi:[1,0]
	v_pk_mul_f32 v[12:13], v[12:13], v[200:201] op_sel_hi:[1,0]
	v_pk_mul_f32 v[10:11], v[10:11], v[200:201] op_sel_hi:[1,0]
	v_pk_mul_f32 v[8:9], v[8:9], v[200:201] op_sel_hi:[1,0]
	v_pk_mul_f32 v[6:7], v[6:7], v[200:201] op_sel_hi:[1,0]
	v_pk_mul_f32 v[4:5], v[4:5], v[200:201] op_sel_hi:[1,0]
	v_pk_mul_f32 v[2:3], v[2:3], v[200:201] op_sel_hi:[1,0]
	v_pk_mul_f32 v[0:1], v[0:1], v[200:201] op_sel_hi:[1,0]
